# one static s_setprio 1 for waves 4-7 at kernel entry, all per-segment priority flips in the GEMM loops deleted (on top of the hand-written P8 epilogue)
# baseline (speedup 1.0000x reference)
; #define LAS __attribute__((address_space(3)))
; __device__ __forceinline__ unsigned xb_add(unsigned* p, unsigned v) { return __hip_atomic_fetch_add(p, v, __ATOMIC_RELAXED, __HIP_MEMORY_SCOPE_AGENT); }
; __device__ __forceinline__ unsigned xb_xcc_id() { return (unsigned)__builtin_amdgcn_s_getreg((3 << 11) | 20) & 0xFu; }
; __device__ __forceinline__ XcdBarrier xcd_barrier_post(unsigned* bar, volatile LAS unsigned* st) {
;     XcdBarrier b; b.bar = bar; b.x = xb_xcc_id(); b.st = st;
;     if (threadIdx.x == 0) (void)xb_add(&bar[XB_XCNT(b.x)], 1u);
;     return b;
; __global__ void __launch_bounds__(512, 2) mk_fwd(Args args) {
;     ...
;     Frame F;
;     F.lds = (LAS unsigned char*)lds_raw; F.tid = threadIdx.x; F.lane = F.tid & 63; F.wave = __builtin_amdgcn_readfirstlane(F.tid >> 6); F.G = gridDim.x;
; #pragma unroll
;     for (int i = 0; i < 30; ++i) F.in[i] = args.in[i];
;     F.out = args.out; F.ws = args.ws;
;     volatile LAS unsigned* MISC = (volatile LAS unsigned*)(F.lds + LDSCTL_OFF);
;     if (F.tid < 64) MISC[F.tid] = 0u;
;     __syncthreads();
;     unsigned* ctl = (unsigned*)(F.ws + WS_CTL);
;     XcdBarrier bar = xcd_barrier_post(ctl + CW_BAR + args.li * XCD_BAR_WORDS, MISC + 8);
_Z6mk_fwd4Args:
	v_readfirstlane_b32 s98, v0
	s_nop 3
	s_and_b32 s98, s98, 0x3ff
	s_lshr_b32 s98, s98, 6
	s_cmp_ge_u32 s98, 4
	s_cbranch_scc0 .Lprio_done
	s_setprio 1
.Lprio_done:
	s_load_dword s96, s[0:1], 0x110
	s_load_dwordx16 s[72:87], s[0:1], 0xc0
	s_mov_b32 s92, s2
	s_add_u32 s2, s0, 0x110
	s_addc_u32 s3, s1, 0
	v_readfirstlane_b32 s94, v0
	v_writelane_b32 v254, s2, 0
	v_cmp_gt_u32_e32 vcc, 64, v0
	s_nop 0
	v_writelane_b32 v254, s3, 1
	s_and_saveexec_b64 s[2:3], vcc
	v_lshl_add_u32 v1, v0, 2, 0
	v_add_u32_e32 v1, 0x27f00, v1
	v_mov_b32_e32 v2, 0
	ds_write_b32 v1, v2
	s_or_b64 exec, exec, s[2:3]
	s_load_dwordx16 s[4:19], s[0:1], 0x0
	s_waitcnt lgkmcnt(0)
	v_writelane_b32 v254, s4, 2
	s_nop 1
	v_writelane_b32 v254, s5, 3
	v_writelane_b32 v254, s6, 4
	v_writelane_b32 v254, s7, 5
	v_writelane_b32 v254, s8, 6
	v_writelane_b32 v254, s9, 7
	v_writelane_b32 v254, s10, 8
	v_writelane_b32 v254, s11, 9
	v_writelane_b32 v254, s12, 10
	v_writelane_b32 v254, s13, 11
	v_writelane_b32 v254, s14, 12
	v_writelane_b32 v254, s15, 13
	v_writelane_b32 v254, s16, 14
	v_writelane_b32 v254, s17, 15
	v_writelane_b32 v254, s18, 16
	v_writelane_b32 v254, s19, 17
	s_load_dword s2, s[0:1], 0x108
	s_load_dwordx16 s[4:19], s[0:1], 0x80
	s_waitcnt lgkmcnt(0)
	s_barrier
	s_mulk_i32 s2, 0xd80
	v_writelane_b32 v254, s4, 18
	s_ashr_i32 s3, s2, 31
	s_lshl_b64 s[2:3], s[2:3], 2
	v_writelane_b32 v254, s5, 19
	v_writelane_b32 v254, s6, 20
	v_writelane_b32 v254, s7, 21
	v_writelane_b32 v254, s8, 22
	v_writelane_b32 v254, s9, 23
	v_writelane_b32 v254, s10, 24
	v_writelane_b32 v254, s11, 25
	v_writelane_b32 v254, s12, 26
	v_writelane_b32 v254, s13, 27
	v_writelane_b32 v254, s14, 28
	v_writelane_b32 v254, s15, 29
	v_writelane_b32 v254, s16, 30
	s_add_u32 s2, s86, s2
	v_writelane_b32 v254, s17, 31
	s_addc_u32 s3, s87, s3
	v_writelane_b32 v254, s18, 32
	s_add_u32 s2, s2, 0x1000
	v_writelane_b32 v254, s19, 33
	s_addc_u32 s3, s3, 0
	v_writelane_b32 v254, s2, 34
	v_cmp_eq_u32_e64 s[4:5], 0, v0
	s_nop 0
	v_writelane_b32 v254, s3, 35
	s_getreg_b32 s2, hwreg(HW_REG_XCC_ID, 0, 4)
	s_and_b32 s2, s2, 15
	v_writelane_b32 v254, s2, 36
	s_mov_b64 s[2:3], exec
	v_writelane_b32 v254, s4, 37
	s_nop 1
	v_writelane_b32 v254, s5, 38
	s_and_b64 s[4:5], s[2:3], s[4:5]
	s_mov_b64 exec, s[4:5]
	s_cbranch_execz .LBB0_5
	s_mov_b64 s[4:5], exec
	v_mbcnt_lo_u32_b32 v1, s4, 0
	v_mbcnt_hi_u32_b32 v1, s5, v1
	v_cmp_eq_u32_e32 vcc, 0, v1
	s_and_b64 s[6:7], exec, vcc
	s_mov_b64 exec, s[6:7]
	s_cbranch_execz .LBB0_5
	v_readlane_b32 s6, v254, 36
	s_bcnt1_i32_b64 s4, s[4:5]
	s_lshl_b32 s6, s6, 8
	v_mov_b32_e32 v2, s4
	v_readlane_b32 s4, v254, 34
	v_mov_b32_e32 v1, s6
	v_readlane_b32 s5, v254, 35
	s_nop 4
	global_atomic_add v1, v2, s[4:5] offset:1024

; __global__ void __launch_bounds__(512, 2) mk_fwd(Args args) {
;     extern __shared__ __attribute__((aligned(16))) unsigned char lds_raw[];
	.amdhsa_kernel _Z6mk_fwd4Args
		.amdhsa_group_segment_fixed_size 0
		.amdhsa_private_segment_fixed_size 0
		.amdhsa_kernarg_size 528
		.amdhsa_user_sgpr_count 2
		.amdhsa_user_sgpr_dispatch_ptr 0
		.amdhsa_user_sgpr_queue_ptr 0
		.amdhsa_user_sgpr_kernarg_segment_ptr 1
		.amdhsa_user_sgpr_dispatch_id 0
		.amdhsa_user_sgpr_kernarg_preload_length 0
		.amdhsa_user_sgpr_kernarg_preload_offset 0
		.amdhsa_user_sgpr_private_segment_size 0
		.amdhsa_uses_dynamic_stack 0
		.amdhsa_enable_private_segment 0
		.amdhsa_system_sgpr_workgroup_id_x 1
		.amdhsa_system_sgpr_workgroup_id_y 0
		.amdhsa_system_sgpr_workgroup_id_z 0
		.amdhsa_system_sgpr_workgroup_info 0
		.amdhsa_system_vgpr_workitem_id 0
		.amdhsa_next_free_vgpr 256
		.amdhsa_next_free_sgpr 102
		.amdhsa_accum_offset 256
		.amdhsa_reserve_vcc 1
		.amdhsa_float_round_mode_32 0
		.amdhsa_float_round_mode_16_64 0
		.amdhsa_float_denorm_mode_32 3
		.amdhsa_float_denorm_mode_16_64 3
		.amdhsa_dx10_clamp 1
		.amdhsa_ieee_mode 1
		.amdhsa_fp16_overflow 0
		.amdhsa_tg_split 0
		.amdhsa_exception_fp_ieee_invalid_op 0
		.amdhsa_exception_fp_denorm_src 0
		.amdhsa_exception_fp_ieee_div_zero 0
		.amdhsa_exception_fp_ieee_overflow 0
		.amdhsa_exception_fp_ieee_underflow 0
		.amdhsa_exception_fp_ieee_inexact 0
		.amdhsa_exception_int_div_zero 0
	.end_amdhsa_kernel

; __global__ void __launch_bounds__(512, 2) mk_fwd(Args args) {
;     extern __shared__ __attribute__((aligned(16))) unsigned char lds_raw[];
amdhsa.kernels:
  - .agpr_count:     0
    .args:
      - .offset:         0
        .size:           272
        .value_kind:     by_value
      - .offset:         272
        .size:           4
        .value_kind:     hidden_block_count_x
      - .offset:         276
        .size:           4
        .value_kind:     hidden_block_count_y
      - .offset:         280
        .size:           4
        .value_kind:     hidden_block_count_z
      - .offset:         284
        .size:           2
        .value_kind:     hidden_group_size_x
      - .offset:         286
        .size:           2
        .value_kind:     hidden_group_size_y
      - .offset:         288
        .size:           2
        .value_kind:     hidden_group_size_z
      - .offset:         290
        .size:           2
        .value_kind:     hidden_remainder_x
      - .offset:         292
        .size:           2
        .value_kind:     hidden_remainder_y
      - .offset:         294
        .size:           2
        .value_kind:     hidden_remainder_z
      - .offset:         312
        .size:           8
        .value_kind:     hidden_global_offset_x
      - .offset:         320
        .size:           8
        .value_kind:     hidden_global_offset_y
      - .offset:         328
        .size:           8
        .value_kind:     hidden_global_offset_z
      - .offset:         336
        .size:           2
        .value_kind:     hidden_grid_dims
      - .offset:         392
        .size:           4
        .value_kind:     hidden_dynamic_lds_size
    .group_segment_fixed_size: 0
    .kernarg_segment_align: 8
    .kernarg_segment_size: 528
    .language:       OpenCL C
    .language_version:
      - 2
      - 0
    .max_flat_workgroup_size: 512
    .name:           _Z6mk_fwd4Args
    .private_segment_fixed_size: 0
    .sgpr_count:     108
    .sgpr_spill_count: 154
    .symbol:         _Z6mk_fwd4Args.kd
    .uniform_work_group_size: 1
    .uses_dynamic_stack: false
    .vgpr_count:     256
    .vgpr_spill_count: 0
    .wavefront_size: 64
